# HBM-bound ret_kv staggered: partial-producer workgroups run it (and their arrival) after their attention work, so only half the chip streams the retention operands at the start of the phase
# speedup vs baseline: 1.0066x; 1.0039x over previous
.LBB0_379:
	s_cmpk_lt_i32 s67, 0x200
	s_cselect_b64 s[0:1], -1, 0
	v_writelane_b32 v254, s0, 62
	s_and_b64 vcc, exec, s[0:1]
	s_waitcnt lgkmcnt(0)
	v_writelane_b32 v254, s1, 63
	s_barrier
	v_mbcnt_lo_u32_b32 v0, -1, 0
	v_mbcnt_hi_u32_b32 v0, -1, v0
	v_lshlrev_b32_e32 v199, 2, v0
	v_readlane_b32 s100, v254, 18
	v_readlane_b32 s101, v254, 19
	s_nop 4
	global_load_dword v200, v199, s[100:101]
	global_load_dword v201, v199, s[100:101] offset:256
	global_load_dword v202, v199, s[100:101] offset:512
	global_load_dword v203, v199, s[100:101] offset:768
	v_readlane_b32 s100, v254, 14
	v_readlane_b32 s101, v254, 15
	s_nop 4
	global_load_dword v204, v199, s[100:101]
	v_readlane_b32 s100, v254, 16
	v_readlane_b32 s101, v254, 17
	s_nop 4
	global_load_dword v205, v199, s[100:101]
	s_cmp_lg_u32 s98, 0
	s_cbranch_scc0 .Lst_norm
	s_cmp_lt_u32 s67, 0x80
	s_cbranch_scc0 .Lst_norm
	s_waitcnt vmcnt(0)
	v_readlane_b32 s0, v254, 25
	s_nop 3
	s_lshl_b32 s12, s0, 4
	s_branch .Lrk_noarr
.Lst_norm:
	s_cbranch_vccnz .LBB0_381
	v_readlane_b32 s0, v254, 25
	s_lshl_b32 s12, s0, 4
	s_cbranch_execz .LBB0_382
	s_waitcnt vmcnt(0)
	s_branch .LBB0_384

.LBB0_469:
	s_cmp_lg_u32 s98, 0
	s_cbranch_scc0 .Lst_skip2
	v_readlane_b32 s67, v255, 10
	s_nop 3
	s_cmp_lt_u32 s67, 0x80
	s_cbranch_scc0 .Lst_skip2
	s_waitcnt vmcnt(0)
	v_readlane_b32 s78, v255, 15
	v_readlane_b32 s44, v254, 61
	v_readlane_b32 s100, v255, 0
	v_readlane_b32 s101, v255, 1
	v_mbcnt_lo_u32_b32 v0, -1, 0
	v_mbcnt_hi_u32_b32 v0, -1, v0
	s_nop 3
	v_readlane_b32 s0, v254, 25
	s_lshl_b32 s12, s0, 4
	s_and_b32 s2, s12, 32
	s_and_b32 s3, s44, 32
	s_lshl_b32 s0, s2, 8
	s_add_u32 s0, s74, s0
	s_addc_u32 s1, s75, 0
	s_lshl_b32 s4, s3, 2
	v_and_b32_e32 v4, 31, v0
	s_add_u32 s0, s0, s4
	s_addc_u32 s1, s1, 0
	v_lshlrev_b32_e32 v16, 2, v4
	v_mov_b32_e32 v17, 0
	v_ashrrev_i32_e32 v5, 5, v0
	v_lshl_add_u64 v[2:3], s[0:1], 0, v[16:17]
	s_mov_b64 s[0:1], 0xe600000
	v_lshlrev_b32_e32 v0, 3, v5
	v_lshl_add_u64 v[18:19], v[2:3], 0, s[0:1]
	v_lshlrev_b32_e32 v20, 8, v5
	v_or_b32_e32 v41, s3, v4
	s_lshl_b32 s0, s67, 1
	v_readlane_b32 s3, v254, 48
	v_ashrrev_i32_e32 v1, 31, v0
	v_add_u32_e32 v22, 0x400, v20
	v_add_u32_e32 v24, 0x440, v20
	v_add_u32_e32 v26, 0x480, v20
	v_add_u32_e32 v28, 0x4c0, v20
	v_add_u32_e32 v30, 0x600, v20
	v_add_u32_e32 v32, 0x640, v20
	v_add_u32_e32 v34, 0x680, v20
	v_add_u32_e32 v36, 0x6c0, v20
	s_add_i32 s0, s3, s0
	s_lshl_b32 s1, s67, 8
	s_lshl_b32 s3, s3, 7
	v_or_b32_e32 v40, s2, v4
	v_ashrrev_i32_e32 v21, 31, v20
	v_ashrrev_i32_e32 v23, 31, v22
	v_ashrrev_i32_e32 v25, 31, v24
	v_ashrrev_i32_e32 v27, 31, v26
	v_ashrrev_i32_e32 v29, 31, v28
	v_ashrrev_i32_e32 v31, 31, v30
	v_ashrrev_i32_e32 v33, 31, v32
	v_ashrrev_i32_e32 v35, 31, v34
	v_ashrrev_i32_e32 v37, 31, v36
	s_lshl_b32 s2, s78, 1
	s_add_i32 s3, s1, s3
	s_lshl_b32 s6, s78, 8
	v_lshlrev_b64 v[38:39], 1, v[0:1]
	s_mov_b64 s[4:5], 0x1000000
	s_mov_b32 s7, 0x1000000
	s_mov_b32 s8, s67
.Lrk2_loop:
	s_ashr_i32 s10, s0, 9
	s_and_b32 s1, s0, 0x1c0
	s_and_b32 s9, s3, 0x1f80
	s_ashr_i32 s11, s10, 31
	v_or_b32_e32 v0, s1, v40
	s_lshl_b32 s9, s9, 1
	v_lshlrev_b32_e32 v16, 15, v0
	s_lshl_b64 s[10:11], s[10:11], 14
	v_lshl_add_u64 v[0:1], s[100:101], 0, v[16:17]
	s_or_b32 s10, s10, s9
	v_or_b32_e32 v2, s1, v41
	v_lshl_add_u64 v[0:1], v[0:1], 0, s[10:11]
	v_lshlrev_b32_e32 v16, 15, v2
	v_lshl_add_u64 v[0:1], v[0:1], 0, v[38:39]
	v_lshl_add_u64 v[2:3], s[100:101], 0, v[16:17]
	v_lshl_add_u64 v[70:71], v[0:1], 0, s[4:5]
	v_add_co_u32_e32 v0, vcc, s7, v0
	v_lshl_add_u64 v[2:3], v[2:3], 0, s[10:11]
	s_nop 0
	v_addc_co_u32_e32 v1, vcc, 0, v1, vcc
	v_lshl_add_u64 v[72:73], v[2:3], 0, v[38:39]
	global_load_dwordx4 v[0:3], v[0:1], off
	s_nop 0
	global_load_dwordx4 v[4:7], v[72:73], off
	global_load_dwordx4 v[42:45], v[70:71], off offset:32
	global_load_dwordx4 v[46:49], v[72:73], off offset:32
	global_load_dwordx4 v[50:53], v[70:71], off offset:64
	global_load_dwordx4 v[54:57], v[70:71], off offset:224
	global_load_dwordx4 v[58:61], v[72:73], off offset:224
	global_load_dwordx4 v[62:65], v[72:73], off offset:64
	global_load_dwordx4 v[66:69], v[70:71], off offset:96
	s_ashr_i32 s1, s0, 31
	s_lshl_b64 s[10:11], s[0:1], 14
	s_add_i32 s8, s8, s78
	s_add_i32 s3, s3, s6
	s_add_i32 s0, s0, s2
	s_cmpk_lt_i32 s8, 0x200
	s_waitcnt vmcnt(7)
	v_mfma_f32_32x32x16_bf16 v[0:15], v[0:3], v[4:7], 0
	s_waitcnt vmcnt(5)
	v_mfma_f32_32x32x16_bf16 v[0:15], v[42:45], v[46:49], v[0:15]
	global_load_dwordx4 v[42:45], v[72:73], off offset:96
	global_load_dwordx4 v[46:49], v[70:71], off offset:128
	s_waitcnt vmcnt(3)
	v_mfma_f32_32x32x16_bf16 v[0:15], v[50:53], v[62:65], v[0:15]
	global_load_dwordx4 v[50:53], v[72:73], off offset:128
	global_load_dwordx4 v[62:65], v[70:71], off offset:160
	s_waitcnt vmcnt(3)
	v_mfma_f32_32x32x16_bf16 v[0:15], v[66:69], v[42:45], v[0:15]
	global_load_dwordx4 v[42:45], v[72:73], off offset:160
	global_load_dwordx4 v[66:69], v[70:71], off offset:192
	s_waitcnt vmcnt(3)
	v_mfma_f32_32x32x16_bf16 v[0:15], v[46:49], v[50:53], v[0:15]
	global_load_dwordx4 v[46:49], v[72:73], off offset:192
	s_waitcnt vmcnt(2)
	v_mfma_f32_32x32x16_bf16 v[0:15], v[62:65], v[42:45], v[0:15]
	v_lshl_add_u64 v[42:43], v[18:19], 0, s[10:11]
	v_lshl_add_u64 v[44:45], v[20:21], 2, v[42:43]
	v_lshl_add_u64 v[50:51], v[22:23], 2, v[42:43]
	v_lshl_add_u64 v[52:53], v[24:25], 2, v[42:43]
	v_lshl_add_u64 v[62:63], v[30:31], 2, v[42:43]
	v_lshl_add_u64 v[64:65], v[32:33], 2, v[42:43]
	s_waitcnt vmcnt(0)
	v_mfma_f32_32x32x16_bf16 v[0:15], v[66:69], v[46:49], v[0:15]
	v_lshl_add_u64 v[46:47], v[26:27], 2, v[42:43]
	v_lshl_add_u64 v[48:49], v[28:29], 2, v[42:43]
	v_lshl_add_u64 v[66:67], v[34:35], 2, v[42:43]
	v_lshl_add_u64 v[42:43], v[36:37], 2, v[42:43]
	v_mfma_f32_32x32x16_bf16 v[0:15], v[54:57], v[58:61], v[0:15]
	s_nop 11
	global_store_dword v[44:45], v0, off
	global_store_dword v[44:45], v1, off offset:256
	global_store_dword v[44:45], v2, off offset:512
	global_store_dword v[44:45], v3, off offset:768
	global_store_dword v[44:45], v4, off offset:2048
	global_store_dword v[44:45], v5, off offset:2304
	global_store_dword v[44:45], v6, off offset:2560
	global_store_dword v[44:45], v7, off offset:2816
	global_store_dword v[50:51], v8, off
	global_store_dword v[52:53], v9, off
	global_store_dword v[46:47], v10, off
	global_store_dword v[48:49], v11, off
	global_store_dword v[62:63], v12, off
	global_store_dword v[64:65], v13, off
	global_store_dword v[66:67], v14, off
	global_store_dword v[42:43], v15, off
	s_cbranch_scc1 .Lrk2_loop
	s_cmp_lg_u32 s98, 0
	s_cbranch_scc0 .Lrk2_noarr
	s_waitcnt vmcnt(0)
	s_barrier
	v_readlane_b32 s99, v254, 25
	v_readlane_b32 s100, v254, 24
	s_nop 3
	s_cmp_lg_u32 s99, 0
	s_cbranch_scc1 .Lrk2_noarr
	s_lshl_b32 s100, s100, 8
	s_add_i32 s100, s100, 0xfa0c100
	v_mov_b32_e32 v0, s100
	v_mov_b32_e32 v1, 1
	s_mov_b64 s[100:101], exec
	s_mov_b64 exec, 1
	v_mov_b32_e32 v3, 0x21000
	ds_read_b32 v3, v3
	global_atomic_add v2, v0, v1, s[74:75] sc0
	s_waitcnt vmcnt(0) lgkmcnt(0)
	v_add_u32_e32 v2, 1, v2
	v_cmp_eq_u32_e32 vcc, v2, v3
	s_cbranch_vccz .Lrk2_arrd
	buffer_wbl2 sc1
	s_waitcnt vmcnt(0)
	v_mov_b32_e32 v0, 0xfa0e000
	global_atomic_add v0, v1, s[74:75]

.Lrk2_noarr:
.Lst_skip2:
	s_waitcnt vmcnt(0)
	v_readlane_b32 s66, v254, 22
	v_readlane_b32 s67, v254, 23
	v_readlane_b32 s72, v255, 2
	v_readlane_b32 s52, v254, 55
	s_and_b64 vcc, exec, s[66:67]
	v_readlane_b32 s70, v255, 10
	v_readlane_b32 s73, v255, 3
	v_readlane_b32 s53, v254, 56
	v_readlane_b32 s42, v254, 50
	s_waitcnt vmcnt(63) expcnt(7) lgkmcnt(15)
	s_barrier
	v_readlane_b32 s43, v254, 51
	s_cbranch_vccnz .LBB0_523
	s_cmp_lg_u32 s98, 0
	s_cbranch_scc0 .Lb3_orig
	s_mov_b64 s[100:101], exec
	s_mov_b64 exec, 1
	v_mov_b32_e32 v0, 0x21004
	ds_read_b32 v1, v0
	v_mov_b32_e32 v0, 0xfa0e000
	s_mov_b32 s99, 0
	s_waitcnt lgkmcnt(0)
	buffer_inv sc1
